# A loop: w0/w1 pack written in place (no v_mov), s_nop pads after max3 removed, T5 bias skipped for tiles wholly beyond |rel|>=1024 (table is identically the far-field constant there)
# speedup vs baseline: 1.0414x; 1.0169x over previous
; #define LAS __attribute__((address_space(3)))
; #define ATT_WAIT_BAR() asm volatile("s_waitcnt vmcnt(0) lgkmcnt(0)\n\ts_barrier" ::: "memory")
; #define SBAR() __builtin_amdgcn_sched_barrier(0)
; #define MF(a_, b_, c_) __builtin_amdgcn_mfma_f32_32x32x16_bf16(a_, b_, c_, 0, 0, 0)
; #define ATT_XLD(so_) do { if (KIND == 2) { const lds_cptr xb_ = shm3 + (so_) + 32768 + r32 * 16; x0 = *(const LAS bf16x8*)(xb_); x1 = *(const LAS bf16x8*)(xb_ + 512); if (hi) { x0 = (bf16x8){0, 0, 0, 0, 0, 0, 0, 0}; x1 = x0; } } } while (0)
; template <int KIND> DI void attn_unit(const Params& P, int b, int h, int qb, char* shm, float lam, bool dry = false) {
;     ...
;     { const bf16_t* qp = P.Qp + (rowbase + qrow0 + r32) * PITCH + qoff + hi * 8;
; #pragma unroll
;       for (int d0 = 0; d0 < 4; ++d0) qr[d0] = *(const bf16x8*)(qp + d0 * 16); }
;     float qkmax = 0.f;
;     if (KIND == 2) { cb = P.CK[(size_t)(b * 8 + h) * SEQ + qrow0 + r32]; const unsigned* np = P.nrm + (b * 8 + h) * 4; qkmax = (sqrtf(__uint_as_float(np[0]) * __uint_as_float(np[2])) + sqrtf(__uint_as_float(np[1]) * __uint_as_float(np[3]))) * 1.001f + 0.01f; }
;     asm volatile("" : "+v"(qr[0]), "+v"(qr[1]), "+v"(qr[2]), "+v"(qr[3]), "+v"(cb), "+v"(qkmax));
;     bf16x8 ones = (bf16x8){0, 0, 0, 0, 0, 0, 0, 0}; if (KIND == 2 && hi == 0) { ones[0] = 0x3F80; ones[1] = 0x3F80; ones[2] = 0x3F80; }
;     float mhat = 0.f, lsum = 0.f; f32x16 o[NDB]; f32x16 negm;
; #pragma unroll
;     for (int i = 0; i < NDB; ++i) o[i] = f32x16{};
; #pragma unroll
;     for (int r = 0; r < 16; ++r) negm[r] = cb;
;     const int vlane = ((lane >> 4) & 1) * 32 + (lane & 3) * 8 + (4 * hi + ((lane & 15) >> 2)) * 64;
;     LAS unsigned* vote = (LAS unsigned*)(shm3 + OFF_VOTE);
;     if (KIND == 2 && tid < 32) vote[tid] = 0u;
;     ATT_WAIT_BAR();
;     int sc = 0, sd = 3 * SLOT;
;     int nt_eff = NT;
;     ...
;     f32x16 pa0, pa1, pb0, pb1;
;     bf16x8 kf[4], x0, x1;
;     ATT_KLD(0, 0); ATT_XLD(0);
;     pa0 = MF(kf[0], qr[0], negm); pa1 = MF(kf[1], qr[0], negm); pa0 = MF(kf[2], qr[1], pa0); pa1 = MF(kf[3], qr[1], pa1);
;     SBAR(); ATT_KLD(0, 1); SBAR();
;     pa0 = MF(kf[0], qr[2], pa0); pa1 = MF(kf[1], qr[2], pa1); pa0 = MF(kf[2], qr[3], pa0); pa1 = MF(kf[3], qr[3], pa1);
;     if (KIND == 2) { pa0 = MF(x0, ones, pa0); pa1 = MF(x1, ones, pa1); }
;     ATT_FIX(pa0, pa1, ATT_TILE(0));
.LBB0_388:
	s_lshl_b32 s2, s3, 7
	s_lshl_b32 s13, s9, 5
	v_lshlrev_b32_sdwa v0, v246, v166 dst_sel:DWORD dst_unused:UNUSED_PAD src0_sel:DWORD src1_sel:BYTE_3
	s_or_b32 s13, s13, s2
	v_and_b32_e32 v191, 31, v36
	s_lshl_b32 s2, s28, 7
	s_lshl_b32 s14, s8, 6
	v_add_u32_e32 v0, s13, v0
	s_add_i32 s14, s14, s2
	v_or_b32_e32 v3, v0, v191
	v_mov_b64_e32 v[0:1], s[36:37]
	v_lshrrev_b32_e32 v198, 5, v195
	v_mad_u64_u32 v[0:1], s[16:17], v3, s86, v[0:1]
	s_ashr_i32 s15, s14, 31
	v_lshl_add_u64 v[6:7], s[14:15], 1, v[0:1]
	v_lshlrev_b32_e32 v192, 4, v198
	v_mov_b32_e32 v193, v2
	v_lshl_add_u64 v[6:7], v[6:7], 0, v[192:193]
	global_load_dwordx4 v[148:151], v[6:7], off offset:96
	global_load_dwordx4 v[152:155], v[6:7], off offset:64
	global_load_dwordx4 v[156:159], v[6:7], off offset:32
	global_load_dwordx4 v[160:163], v[6:7], off
	s_lshl_b32 s14, s8, 13
	v_mov_b32_e32 v3, v2
	s_add_i32 s14, s14, 0
	v_lshlrev_b32_e32 v5, 10, v198
	v_lshlrev_b32_e32 v6, 4, v191
	v_add3_u32 v193, s14, v5, v6
	s_waitcnt vmcnt(0)
	s_waitcnt vmcnt(0) lgkmcnt(0)
	s_barrier
	ds_read_b128 v[42:45], v193
	v_mov_b32_e32 v5, v4
	v_mov_b32_e32 v6, v4
	v_mov_b32_e32 v7, v4
	v_mov_b32_e32 v8, v4
	v_mov_b32_e32 v9, v4
	v_mov_b32_e32 v10, v4
	v_mov_b32_e32 v11, v4
	v_mov_b32_e32 v12, v4
	v_mov_b32_e32 v13, v4
	v_mov_b32_e32 v14, v4
	v_mov_b32_e32 v15, v4
	v_mov_b32_e32 v16, v4
	v_mov_b32_e32 v17, v4
	v_mov_b32_e32 v18, v4
	v_mov_b32_e32 v19, v4
	v_lshlrev_b32_e32 v3, 2, v198
	s_waitcnt lgkmcnt(0)
	v_mfma_f32_32x32x16_bf16 v[20:35], v[42:45], v[160:163], v[4:19]
	ds_read_b128 v[42:45], v193 offset:512
	s_waitcnt lgkmcnt(0)
	v_mfma_f32_32x32x16_bf16 v[84:99], v[42:45], v[160:163], v[4:19]
	ds_read_b128 v[42:45], v193 offset:2048
	s_waitcnt lgkmcnt(0)
	v_mfma_f32_32x32x16_bf16 v[20:35], v[42:45], v[156:159], v[20:35]
	ds_read_b128 v[42:45], v193 offset:2560
	s_waitcnt lgkmcnt(0)
	v_mfma_f32_32x32x16_bf16 v[84:99], v[42:45], v[156:159], v[84:99]
	ds_read_b128 v[42:45], v193 offset:4096
	ds_read_b128 v[46:49], v193 offset:4608
	ds_read_b128 v[50:53], v193 offset:6144
	ds_read_b128 v[54:57], v193 offset:6656
	s_waitcnt lgkmcnt(3)
	v_mfma_f32_32x32x16_bf16 v[20:35], v[42:45], v[152:155], v[20:35]
	s_cmpk_gt_u32 s13, 0x43e
	s_waitcnt lgkmcnt(2)
	v_mfma_f32_32x32x16_bf16 v[84:99], v[46:49], v[152:155], v[84:99]
	s_waitcnt lgkmcnt(1)
	v_mfma_f32_32x32x16_bf16 v[20:35], v[50:53], v[148:151], v[20:35]
	s_waitcnt lgkmcnt(0)
	v_mfma_f32_32x32x16_bf16 v[84:99], v[54:57], v[148:151], v[84:99]
	s_cbranch_scc1 .LBB0_390
	v_or_b32_e32 v37, s13, v191
	v_sub_u32_e32 v37, v3, v37
	s_add_i32 s14, 0, 0x21000
	v_lshl_add_u32 v37, v37, 2, s14
	v_add_u32_e32 v42, 0x20fc, v37
	v_add_u32_e32 v44, 0x217c, v37
	ds_read2_b32 v[42:43], v42 offset1:1
	ds_read2_b32 v[44:45], v44 offset1:1
	v_add_u32_e32 v46, 0x2104, v37
	v_add_u32_e32 v48, 0x2184, v37
	v_add_u32_e32 v50, 0x211c, v37
	v_add_u32_e32 v52, 0x219c, v37
	v_add_u32_e32 v54, 0x2124, v37
	v_add_u32_e32 v56, 0x21a4, v37
	v_add_u32_e32 v58, 0x213c, v37
	v_add_u32_e32 v60, 0x21bc, v37
	v_add_u32_e32 v62, 0x2144, v37
	v_add_u32_e32 v64, 0x21c4, v37
	v_add_u32_e32 v66, 0x215c, v37
	v_add_u32_e32 v68, 0x21dc, v37
	v_add_u32_e32 v70, 0x2164, v37
	v_add_u32_e32 v37, 0x21e4, v37
	ds_read2_b32 v[46:47], v46 offset1:1
	ds_read2_b32 v[48:49], v48 offset1:1
	ds_read2_b32 v[50:51], v50 offset1:1
	ds_read2_b32 v[52:53], v52 offset1:1
	ds_read2_b32 v[54:55], v54 offset1:1
	ds_read2_b32 v[56:57], v56 offset1:1
	ds_read2_b32 v[58:59], v58 offset1:1
	ds_read2_b32 v[60:61], v60 offset1:1
	ds_read2_b32 v[62:63], v62 offset1:1
	ds_read2_b32 v[64:65], v64 offset1:1
	ds_read2_b32 v[66:67], v66 offset1:1
	ds_read2_b32 v[68:69], v68 offset1:1
	ds_read2_b32 v[70:71], v70 offset1:1
	s_waitcnt lgkmcnt(14)
	v_pk_add_f32 v[20:21], v[20:21], v[42:43]
	ds_read2_b32 v[42:43], v37 offset1:1
	s_waitcnt lgkmcnt(3)
	v_pk_add_f32 v[32:33], v[32:33], v[66:67]
	v_pk_add_f32 v[30:31], v[30:31], v[62:63]
	s_waitcnt lgkmcnt(1)
	v_pk_add_f32 v[34:35], v[34:35], v[70:71]
	v_pk_add_f32 v[28:29], v[28:29], v[58:59]
	v_pk_add_f32 v[26:27], v[26:27], v[54:55]
	v_pk_add_f32 v[24:25], v[24:25], v[50:51]
	v_pk_add_f32 v[22:23], v[22:23], v[46:47]
	s_waitcnt lgkmcnt(0)
	v_pk_add_f32 v[98:99], v[98:99], v[42:43]
	v_pk_add_f32 v[96:97], v[96:97], v[68:69]
	v_pk_add_f32 v[94:95], v[94:95], v[64:65]
	v_pk_add_f32 v[92:93], v[92:93], v[60:61]
	v_pk_add_f32 v[90:91], v[90:91], v[56:57]
	v_pk_add_f32 v[88:89], v[88:89], v[52:53]
	v_pk_add_f32 v[86:87], v[86:87], v[48:49]
	v_pk_add_f32 v[84:85], v[84:85], v[44:45]

; template <int KIND> DI void attn_unit(const Params& P, int b, int h, int qb, char* shm, float lam, bool dry = false) {
;     ...
;     for (int i = 0; i < nt_eff; ++i) {
;         ATT_STEP_BAR(i);
;         const int sn = (sc == 3 * SLOT) ? 0 : sc + SLOT;
;         const lds_cptr vp = shm3 + sc + 16384 + vlane;
;         bf16x8 vq[4]; bf16x8 pw[4]; u32x4 w0, w1; float sacc = 0.f;
;     ...
;         ATT_KLD(sn, 0); ATT_XLD(sn);
;         SBAR();
;     ...
;         G1(pb0 = MF(kf[0], qr[0], negm), 0, w0, 0);  G1(pb1 = MF(kf[1], qr[0], negm), 2, w0, 1);
;         G1(pb0 = MF(kf[2], qr[1], pb0), 4, w0, 2);   G1(pb1 = MF(kf[3], qr[1], pb1), 6, w0, 3);
;         ATT_KLD(sn, 1);
;         SBAR();
;         G1(pb0 = MF(kf[0], qr[2], pb0), 8, w1, 0);   G1(pb1 = MF(kf[1], qr[2], pb1), 10, w1, 1);
;         LDV(0); SBAR();
;         G1(pb0 = MF(kf[2], qr[3], pb0), 12, w1, 2);
;         LDV(1); SBAR();
;         G1(pb1 = MF(kf[3], qr[3], pb1), 14, w1, 3);
;         LDV(2); SBAR();
;     ...
;         if (KIND == 2) { pb0 = MF(x0, ones, pb0); pb1 = MF(x1, ones, pb1); }
;         pw[0] = __builtin_bit_cast(bf16x8, w0); pw[1] = __builtin_bit_cast(bf16x8, w1);
;     ...
;         if (NDB == 4) {
;             LDV(3); PVM(0); E4(0, w0, 0); PIN(pa1); PIN(sacc); PIN(w0); SBAR();
;             LDV(4); PVM(1); E4(2, w0, 1); PIN(pa1); PIN(sacc); PIN(w0); SBAR();
;             LDV(5); PVM(2); E4(4, w0, 2); PIN(pa1); PIN(sacc); PIN(w0); SBAR();
;             LDV(6); PVM(3); E4(6, w0, 3); PIN(pa1); PIN(sacc); PIN(w0); SBAR();
;             LDV(7); PVM(4); E4(8, w1, 0); PIN(pa1); PIN(sacc); PIN(w1); SBAR();
;             LDV(8); PVM(5); E4(10, w1, 1); PIN(pa1); PIN(sacc); PIN(w1); SBAR();
;             LDV(9); PVM(6); E4(12, w1, 2); PIN(pa1); PIN(sacc); PIN(w1); SBAR();
;             LDV(10); PVM(7); E4(14, w1, 3); PIN(pa1); PIN(sacc); PIN(w1); SBAR();
;         } else {
;             LDV(3); PVM(0); E4(0, w0, 0); E4(2, w0, 1); PIN(pa1); PIN(sacc); PIN(w0); SBAR();
;             LDV(4); PVM(1); E4(4, w0, 2); E4(6, w0, 3); PIN(pa1); PIN(sacc); PIN(w0); SBAR();
;             LDV(5); PVM(2); E4(8, w1, 0); E4(10, w1, 1); PIN(pa1); PIN(sacc); PIN(w1); SBAR();
;             LDV(6); PVM(3); E4(12, w1, 2); E4(14, w1, 3); PIN(pa1); PIN(sacc); PIN(w1); SBAR();
;         }
;     ...
;         pw[2] = __builtin_bit_cast(bf16x8, w0); pw[3] = __builtin_bit_cast(bf16x8, w1);
;         lsum += sacc;
;         ATT_FIX(pb0, pb1, ATT_TILE(i + 1));
.LBB0_395:
	v_lshlrev_b32_e32 v37, 1, v36
	v_lshlrev_b32_e32 v38, 3, v36
	v_lshrrev_b32_e32 v36, 2, v36
	v_and_b32_e32 v37, 32, v37
	v_and_or_b32 v36, v36, 3, v3
	v_and_b32_e32 v38, 24, v38
	v_lshlrev_b32_e32 v36, 6, v36
	v_add_u32_e32 v37, 0, v37
	v_add3_u32 v196, v37, v38, v36
	ds_read_b128 v[36:39], v193 offset:33792
	ds_read_b128 v[40:43], v193 offset:34304
	ds_read_b128 v[44:47], v193 offset:35840
	ds_read_b128 v[48:51], v193 offset:36352
	v_mov_b32_e32 v101, v100
	v_mov_b32_e32 v102, v100
	v_mov_b32_e32 v103, v100
	v_mov_b32_e32 v104, v100
	v_mov_b32_e32 v105, v100
	v_mov_b32_e32 v106, v100
	v_mov_b32_e32 v107, v100
	v_mov_b32_e32 v108, v100
	v_mov_b32_e32 v109, v100
	v_mov_b32_e32 v110, v100
	v_mov_b32_e32 v111, v100
	v_mov_b32_e32 v112, v100
	v_mov_b32_e32 v113, v100
	v_mov_b32_e32 v114, v100
	v_mov_b32_e32 v115, v100
	s_waitcnt lgkmcnt(3)
	v_mfma_f32_32x32x16_bf16 v[116:131], v[36:39], v[160:163], v[4:19]
	v_exp_f32_e32 v20, v20
	v_exp_f32_e32 v21, v21
	v_add_f32_e32 v36, 0, v20
	v_cvt_pk_bf16_f32 v168, v20, v21
	v_add_f32_e32 v36, v21, v36
	v_mov_b32_e32 v169, v168
	v_mov_b32_e32 v170, v168
	v_mov_b32_e32 v171, v168
	s_waitcnt lgkmcnt(2)
	v_mfma_f32_32x32x16_bf16 v[132:147], v[40:43], v[160:163], v[4:19]
	v_exp_f32_e32 v22, v22
	v_exp_f32_e32 v23, v23
	v_add_f32_e32 v36, v36, v22
	v_add_f32_e32 v36, v23, v36
	v_cvt_pk_bf16_f32 v169, v22, v23
	s_waitcnt lgkmcnt(1)
	v_mfma_f32_32x32x16_bf16 v[116:131], v[44:47], v[156:159], v[116:131]
	v_exp_f32_e32 v24, v24
	v_exp_f32_e32 v25, v25
	v_add_f32_e32 v36, v36, v24
	v_add_f32_e32 v36, v25, v36
	v_cvt_pk_bf16_f32 v170, v24, v25
	s_waitcnt lgkmcnt(0)
	v_mfma_f32_32x32x16_bf16 v[132:147], v[48:51], v[156:159], v[132:147]
	v_exp_f32_e32 v26, v26
	v_exp_f32_e32 v27, v27
	v_add_f32_e32 v36, v36, v26
	v_add_f32_e32 v52, v27, v36
	v_cvt_pk_bf16_f32 v171, v26, v27
	ds_read_b128 v[36:39], v193 offset:37888
	ds_read_b128 v[40:43], v193 offset:38400
	ds_read_b128 v[44:47], v193 offset:39936
	ds_read_b128 v[48:51], v193 offset:40448
	s_waitcnt lgkmcnt(3)
	v_mfma_f32_32x32x16_bf16 v[116:131], v[36:39], v[152:155], v[116:131]
	v_exp_f32_e32 v28, v28
	v_exp_f32_e32 v29, v29
	v_add_f32_e32 v36, v52, v28
	v_cvt_pk_bf16_f32 v184, v28, v29
	v_add_f32_e32 v36, v29, v36
	v_mov_b32_e32 v185, v184
	v_mov_b32_e32 v186, v184
	v_mov_b32_e32 v187, v184
	s_waitcnt lgkmcnt(2)
	v_mfma_f32_32x32x16_bf16 v[132:147], v[40:43], v[152:155], v[132:147]
	v_exp_f32_e32 v30, v30
	v_exp_f32_e32 v31, v31
	v_add_f32_e32 v36, v36, v30
	v_add_f32_e32 v40, v31, v36
	v_cvt_pk_bf16_f32 v185, v30, v31
	ds_read_b64_tr_b16 v[36:37], v196 offset:16384
	ds_read_b64_tr_b16 v[38:39], v196 offset:16896
	s_waitcnt lgkmcnt(3)
	v_mfma_f32_32x32x16_bf16 v[116:131], v[44:47], v[148:151], v[116:131]
	v_exp_f32_e32 v32, v32
	v_exp_f32_e32 v33, v33
	v_add_f32_e32 v40, v40, v32
	v_add_f32_e32 v44, v33, v40
	v_cvt_pk_bf16_f32 v186, v32, v33
	ds_read_b64_tr_b16 v[40:41], v196 offset:20480
	ds_read_b64_tr_b16 v[42:43], v196 offset:20992
	s_waitcnt lgkmcnt(4)
	v_mfma_f32_32x32x16_bf16 v[132:147], v[48:51], v[148:151], v[132:147]
	v_exp_f32_e32 v34, v34
	v_exp_f32_e32 v35, v35
	v_add_f32_e32 v44, v44, v34
	v_add_f32_e32 v44, v35, v44
	v_cvt_pk_bf16_f32 v187, v34, v35
	ds_read_b64_tr_b16 v[20:21], v196 offset:24576
	ds_read_b64_tr_b16 v[22:23], v196 offset:25088
	s_waitcnt lgkmcnt(4)
	v_mfma_f32_32x32x16_bf16 v[68:83], v[36:39], v[168:171], v[100:115]
	v_exp_f32_e32 v84, v84
	v_exp_f32_e32 v85, v85
	ds_read_b64_tr_b16 v[172:173], v196 offset:28672
	ds_read_b64_tr_b16 v[174:175], v196 offset:29184
	v_mov_b64_e32 v[164:165], v[168:169]
	v_add_f32_e32 v24, v84, v44
	v_cvt_pk_bf16_f32 v25, v84, v85
	v_add_f32_e32 v24, v85, v24
	v_mov_b64_e32 v[166:167], v[170:171]
	v_mov_b32_e32 v164, v25
	s_waitcnt lgkmcnt(4)
	v_mfma_f32_32x32x16_bf16 v[52:67], v[40:43], v[168:171], v[100:115]
	v_exp_f32_e32 v86, v86
	v_exp_f32_e32 v87, v87
	ds_read_b64_tr_b16 v[176:177], v196 offset:17408
	ds_read_b64_tr_b16 v[178:179], v196 offset:17920
	v_add_f32_e32 v24, v24, v86
	v_add_f32_e32 v24, v87, v24
	v_cvt_pk_bf16_f32 v165, v86, v87
	s_waitcnt lgkmcnt(4)
	v_mfma_f32_32x32x16_bf16 v[36:51], v[20:23], v[168:171], v[100:115]
	v_exp_f32_e32 v88, v88
	v_exp_f32_e32 v89, v89
	ds_read_b64_tr_b16 v[180:181], v196 offset:21504
	ds_read_b64_tr_b16 v[182:183], v196 offset:22016
	v_add_f32_e32 v24, v24, v88
	v_add_f32_e32 v197, v89, v24
	v_cvt_pk_bf16_f32 v166, v88, v89
	v_mov_b64_e32 v[20:21], v[100:101]
	v_mov_b64_e32 v[22:23], v[102:103]
	v_mov_b64_e32 v[24:25], v[104:105]
	v_mov_b64_e32 v[26:27], v[106:107]
	v_mov_b64_e32 v[28:29], v[108:109]
	v_mov_b64_e32 v[30:31], v[110:111]
	v_mov_b64_e32 v[32:33], v[112:113]
	v_mov_b64_e32 v[34:35], v[114:115]
	v_exp_f32_e32 v90, v90
	ds_read_b64_tr_b16 v[214:215], v196 offset:25600
	ds_read_b64_tr_b16 v[216:217], v196 offset:26112
	s_waitcnt lgkmcnt(6)
	v_mfma_f32_32x32x16_bf16 v[20:35], v[172:175], v[168:171], v[20:35]
	v_exp_f32_e32 v91, v91
	v_add_f32_e32 v101, v197, v90
	v_add_f32_e32 v101, v91, v101
	v_cvt_pk_bf16_f32 v167, v90, v91
	s_waitcnt lgkmcnt(4)
	v_mfma_f32_32x32x16_bf16 v[68:83], v[176:179], v[184:187], v[68:83]
	v_exp_f32_e32 v92, v92
	v_exp_f32_e32 v93, v93
	ds_read_b64_tr_b16 v[102:103], v196 offset:29696
	ds_read_b64_tr_b16 v[104:105], v196 offset:30208
	v_mov_b64_e32 v[168:169], v[184:185]
	v_add_f32_e32 v101, v101, v92
	v_cvt_pk_bf16_f32 v106, v92, v93
	v_add_f32_e32 v101, v93, v101
	v_mov_b64_e32 v[170:171], v[186:187]
	v_mov_b32_e32 v168, v106
	s_waitcnt lgkmcnt(4)
	v_mfma_f32_32x32x16_bf16 v[52:67], v[180:183], v[184:187], v[52:67]
	v_exp_f32_e32 v94, v94
	ds_read_b64_tr_b16 v[172:173], v196 offset:18432
	ds_read_b64_tr_b16 v[174:175], v196 offset:18944
	v_exp_f32_e32 v95, v95
	v_add_f32_e32 v101, v101, v94
	v_add_f32_e32 v101, v95, v101
	v_cvt_pk_bf16_f32 v169, v94, v95
	s_waitcnt lgkmcnt(4)
	v_mfma_f32_32x32x16_bf16 v[36:51], v[214:217], v[184:187], v[36:51]
	v_exp_f32_e32 v96, v96
	ds_read_b64_tr_b16 v[176:177], v196 offset:22528
	ds_read_b64_tr_b16 v[178:179], v196 offset:23040
	v_exp_f32_e32 v97, v97
	v_add_f32_e32 v101, v101, v96
	v_add_f32_e32 v101, v97, v101
	v_cvt_pk_bf16_f32 v170, v96, v97
	s_waitcnt lgkmcnt(4)
	v_mfma_f32_32x32x16_bf16 v[20:35], v[102:105], v[184:187], v[20:35]
	v_exp_f32_e32 v98, v98
	ds_read_b64_tr_b16 v[180:181], v196 offset:26624
	ds_read_b64_tr_b16 v[182:183], v196 offset:27136
	v_exp_f32_e32 v99, v99
	v_add_f32_e32 v101, v101, v98
	v_add_f32_e32 v101, v99, v101
	v_cvt_pk_bf16_f32 v171, v98, v99
	s_cmpk_gt_u32 s13, 0x47e
	s_cbranch_scc1 .LBB0_397
	v_or_b32_e32 v84, s13, v191
	v_sub_u32_e32 v84, v3, v84
	s_add_i32 s6, 0, 0x21000
	v_lshl_add_u32 v114, v84, 2, s6
	v_add_u32_e32 v84, 0x21fc, v114
	v_add_u32_e32 v86, 0x227c, v114
	ds_read2_b32 v[84:85], v84 offset1:1
	ds_read2_b32 v[86:87], v86 offset1:1
	v_add_u32_e32 v88, 0x2204, v114
	v_add_u32_e32 v90, 0x2284, v114
	v_add_u32_e32 v92, 0x221c, v114
	v_add_u32_e32 v94, 0x229c, v114
	v_add_u32_e32 v96, 0x2224, v114
	v_add_u32_e32 v98, 0x22a4, v114
	v_add_u32_e32 v102, 0x223c, v114
	v_add_u32_e32 v104, 0x22bc, v114
	v_add_u32_e32 v106, 0x2244, v114
	v_add_u32_e32 v108, 0x22c4, v114
	v_add_u32_e32 v110, 0x225c, v114
	v_add_u32_e32 v112, 0x22dc, v114
	v_add_u32_e32 v115, 0x2264, v114
	v_add_u32_e32 v184, 0x22e4, v114
	ds_read2_b32 v[88:89], v88 offset1:1
	ds_read2_b32 v[90:91], v90 offset1:1
	ds_read2_b32 v[92:93], v92 offset1:1
	ds_read2_b32 v[94:95], v94 offset1:1
	ds_read2_b32 v[96:97], v96 offset1:1
	ds_read2_b32 v[98:99], v98 offset1:1
	ds_read2_b32 v[102:103], v102 offset1:1
	ds_read2_b32 v[104:105], v104 offset1:1
	ds_read2_b32 v[106:107], v106 offset1:1
	ds_read2_b32 v[108:109], v108 offset1:1
	ds_read2_b32 v[110:111], v110 offset1:1
	ds_read2_b32 v[112:113], v112 offset1:1
	ds_read2_b32 v[114:115], v115 offset1:1
	s_waitcnt lgkmcnt(14)
	v_pk_add_f32 v[116:117], v[116:117], v[84:85]
	ds_read2_b32 v[84:85], v184 offset1:1
	s_waitcnt lgkmcnt(3)
	v_pk_add_f32 v[128:129], v[128:129], v[110:111]
	v_pk_add_f32 v[126:127], v[126:127], v[106:107]
	s_waitcnt lgkmcnt(1)
	v_pk_add_f32 v[130:131], v[130:131], v[114:115]
	v_pk_add_f32 v[124:125], v[124:125], v[102:103]
	v_pk_add_f32 v[122:123], v[122:123], v[96:97]
	v_pk_add_f32 v[120:121], v[120:121], v[92:93]
	v_pk_add_f32 v[118:119], v[118:119], v[88:89]
	s_waitcnt lgkmcnt(0)
	v_pk_add_f32 v[146:147], v[146:147], v[84:85]
	v_pk_add_f32 v[144:145], v[144:145], v[112:113]
	v_pk_add_f32 v[142:143], v[142:143], v[108:109]
	v_pk_add_f32 v[140:141], v[140:141], v[104:105]
	v_pk_add_f32 v[138:139], v[138:139], v[98:99]
	v_pk_add_f32 v[136:137], v[136:137], v[94:95]
	v_pk_add_f32 v[134:135], v[134:135], v[90:91]
	v_pk_add_f32 v[132:133], v[132:133], v[86:87]

.LBB0_399:
	s_cmp_lg_u32 0, -1
	v_lshlrev_b32_e32 v116, 2, v191
	s_cselect_b32 s15, 0, 0
	v_sub_u32_e32 v116, v192, v116
	s_lshl_b32 s19, s9, 7
	s_add_i32 s11, s11, s15
	v_subrev_u32_e32 v116, s19, v116
	s_lshl_b32 s3, s3, 9
	s_add_i32 s15, s11, 0x2000
	s_add_i32 s16, s11, 0x4000
	s_add_i32 s17, s11, 0x6000
	s_add_i32 s18, s6, 2
	s_addk_i32 s13, 0xfbc1
	v_subrev_u32_e32 v116, s3, v116
	s_add_i32 s3, 0, 0x232fc
	s_add_u32 s10, s29, s10
	s_addc_u32 s19, s38, 0
	s_add_u32 s0, s10, s0
	v_mov_b32_e32 v191, v2
	s_addc_u32 s1, s19, s1
	v_lshl_add_u64 v[184:185], s[0:1], 0, v[190:191]
	s_lshl_b32 s0, s12, 4
	s_and_b32 s0, s0, 0xc00
	s_add_u32 s0, s4, s0
	s_addc_u32 s1, s5, 0
	s_add_u32 s0, s39, s0
	s_addc_u32 s1, s40, s1
	v_lshlrev_b32_e32 v198, 3, v198
	s_mov_b32 s14, 0
	v_add_u32_e32 v192, s3, v116
	s_mov_b32 s3, 1
	v_lshl_add_u64 v[186:187], s[0:1], 0, v[190:191]
	s_mov_b32 s5, 0x8400
	s_movk_i32 s4, 0x80
	s_cmp_ge_u32 s3, s6
	s_mov_b64 s[0:1], -1
	s_cbranch_scc0 .LBB0_410

; #define SBAR() __builtin_amdgcn_sched_barrier(0)
; #define PIN(x) asm volatile("" : "+v"(x))
; #define MF(a_, b_, c_) __builtin_amdgcn_mfma_f32_32x32x16_bf16(a_, b_, c_, 0, 0, 0)
; #define PVM(j_) o[(j_) % NDB] = MF(vq[(j_) & 3], pw[(j_) / NDB], o[(j_) % NDB])
; template <int KIND> DI void attn_unit(const Params& P, int b, int h, int qb, char* shm, float lam, bool dry = false) {
;     ...
;         ATT_KLD(sn, 0); ATT_XLD(sn);
;         SBAR();
;     ...
;         G1(pb0 = MF(kf[0], qr[0], negm), 0, w0, 0);  G1(pb1 = MF(kf[1], qr[0], negm), 2, w0, 1);
;         G1(pb0 = MF(kf[2], qr[1], pb0), 4, w0, 2);   G1(pb1 = MF(kf[3], qr[1], pb1), 6, w0, 3);
;         ATT_KLD(sn, 1);
;         SBAR();
;         G1(pb0 = MF(kf[0], qr[2], pb0), 8, w1, 0);   G1(pb1 = MF(kf[1], qr[2], pb1), 10, w1, 1);
;         LDV(0); SBAR();
;         G1(pb0 = MF(kf[2], qr[3], pb0), 12, w1, 2);
;         LDV(1); SBAR();
;         G1(pb1 = MF(kf[3], qr[3], pb1), 14, w1, 3);
;         LDV(2); SBAR();
;     ...
;         if (KIND == 2) { pb0 = MF(x0, ones, pb0); pb1 = MF(x1, ones, pb1); }
;         pw[0] = __builtin_bit_cast(bf16x8, w0); pw[1] = __builtin_bit_cast(bf16x8, w1);
;     ...
;         if (NDB == 4) {
;             LDV(3); PVM(0); E4(0, w0, 0); PIN(pa1); PIN(sacc); PIN(w0); SBAR();
;             LDV(4); PVM(1); E4(2, w0, 1); PIN(pa1); PIN(sacc); PIN(w0); SBAR();
;             LDV(5); PVM(2); E4(4, w0, 2); PIN(pa1); PIN(sacc); PIN(w0); SBAR();
;             LDV(6); PVM(3); E4(6, w0, 3); PIN(pa1); PIN(sacc); PIN(w0); SBAR();
;             LDV(7); PVM(4); E4(8, w1, 0); PIN(pa1); PIN(sacc); PIN(w1); SBAR();
;             LDV(8); PVM(5); E4(10, w1, 1); PIN(pa1); PIN(sacc); PIN(w1); SBAR();
;             LDV(9); PVM(6); E4(12, w1, 2); PIN(pa1); PIN(sacc); PIN(w1); SBAR();
;             LDV(10); PVM(7); E4(14, w1, 3); PIN(pa1); PIN(sacc); PIN(w1); SBAR();
;         } else {
;             LDV(3); PVM(0); E4(0, w0, 0); E4(2, w0, 1); PIN(pa1); PIN(sacc); PIN(w0); SBAR();
;             LDV(4); PVM(1); E4(4, w0, 2); E4(6, w0, 3); PIN(pa1); PIN(sacc); PIN(w0); SBAR();
;             LDV(5); PVM(2); E4(8, w1, 0); E4(10, w1, 1); PIN(pa1); PIN(sacc); PIN(w1); SBAR();
;             LDV(6); PVM(3); E4(12, w1, 2); E4(14, w1, 3); PIN(pa1); PIN(sacc); PIN(w1); SBAR();
;         }
;     ...
;         pw[2] = __builtin_bit_cast(bf16x8, w0); pw[3] = __builtin_bit_cast(bf16x8, w1);
;         lsum += sacc;
.LBB0_403:
	s_add_i32 s0, s5, 0x8400
	s_cmp_lg_u32 s5, 0x18c00
	s_cselect_b32 s0, s0, 0
	v_add_u32_e32 v168, s0, v193
	ds_read_b128 v[132:135], v168
	ds_read_b128 v[172:175], v168 offset:512
	ds_read_b128 v[176:179], v168 offset:2048
	ds_read_b128 v[180:183], v168 offset:2560
	v_add_u32_e32 v190, s5, v196
	s_waitcnt lgkmcnt(3)
	v_mfma_f32_32x32x16_bf16 v[116:131], v[132:135], v[160:163], v[4:19]
	v_exp_f32_e32 v100, v100
	v_exp_f32_e32 v101, v101
	v_add_f32_e32 v132, 0, v100
	v_add_f32_e32 v191, v101, v132
	v_cvt_pk_bf16_f32 v164, v100, v101
	s_waitcnt lgkmcnt(2)
	v_mfma_f32_32x32x16_bf16 v[132:147], v[172:175], v[160:163], v[4:19]
	v_exp_f32_e32 v102, v102
	v_exp_f32_e32 v103, v103
	v_add_f32_e32 v165, v191, v102
	v_add_f32_e32 v172, v103, v165
	v_cvt_pk_bf16_f32 v165, v102, v103
	s_waitcnt lgkmcnt(1)
	v_mfma_f32_32x32x16_bf16 v[116:131], v[176:179], v[156:159], v[116:131]
	v_exp_f32_e32 v104, v104
	v_exp_f32_e32 v105, v105
	v_add_f32_e32 v166, v172, v104
	v_add_f32_e32 v172, v105, v166
	v_cvt_pk_bf16_f32 v166, v104, v105
	s_waitcnt lgkmcnt(0)
	v_mfma_f32_32x32x16_bf16 v[132:147], v[180:183], v[156:159], v[132:147]
	v_exp_f32_e32 v106, v106
	v_exp_f32_e32 v107, v107
	v_add_f32_e32 v167, v172, v106
	v_add_f32_e32 v191, v107, v167
	v_cvt_pk_bf16_f32 v167, v106, v107
	ds_read_b128 v[172:175], v168 offset:4096
	ds_read_b128 v[176:179], v168 offset:4608
	ds_read_b128 v[180:183], v168 offset:6144
	ds_read_b128 v[214:217], v168 offset:6656
	s_waitcnt lgkmcnt(3)
	v_mfma_f32_32x32x16_bf16 v[116:131], v[172:175], v[152:155], v[116:131]
	v_exp_f32_e32 v108, v108
	v_exp_f32_e32 v109, v109
	v_add_f32_e32 v168, v191, v108
	v_add_f32_e32 v172, v109, v168
	v_cvt_pk_bf16_f32 v168, v108, v109
	s_waitcnt lgkmcnt(2)
	v_mfma_f32_32x32x16_bf16 v[132:147], v[176:179], v[152:155], v[132:147]
	v_exp_f32_e32 v110, v110
	v_exp_f32_e32 v111, v111
	v_add_f32_e32 v169, v172, v110
	v_add_f32_e32 v176, v111, v169
	v_cvt_pk_bf16_f32 v169, v110, v111
	ds_read_b64_tr_b16 v[172:173], v190 offset:16384
	ds_read_b64_tr_b16 v[174:175], v190 offset:16896
	s_waitcnt lgkmcnt(3)
	v_mfma_f32_32x32x16_bf16 v[116:131], v[180:183], v[148:151], v[116:131]
	v_exp_f32_e32 v112, v112
	v_exp_f32_e32 v113, v113
	v_add_f32_e32 v170, v176, v112
	v_add_f32_e32 v180, v113, v170
	v_cvt_pk_bf16_f32 v170, v112, v113
	ds_read_b64_tr_b16 v[176:177], v190 offset:20480
	ds_read_b64_tr_b16 v[178:179], v190 offset:20992
	s_waitcnt lgkmcnt(4)
	v_mfma_f32_32x32x16_bf16 v[132:147], v[214:217], v[148:151], v[132:147]
	v_exp_f32_e32 v114, v114
	v_exp_f32_e32 v115, v115
	v_add_f32_e32 v171, v180, v114
	v_add_f32_e32 v180, v115, v171
	v_cvt_pk_bf16_f32 v171, v114, v115
	ds_read_b64_tr_b16 v[100:101], v190 offset:24576
	ds_read_b64_tr_b16 v[102:103], v190 offset:25088
	s_waitcnt lgkmcnt(4)
	v_mfma_f32_32x32x16_bf16 v[68:83], v[172:175], v[164:167], v[68:83]
	v_exp_f32_e32 v84, v84
	v_exp_f32_e32 v85, v85
	ds_read_b64_tr_b16 v[104:105], v190 offset:28672
	ds_read_b64_tr_b16 v[106:107], v190 offset:29184
	v_add_f32_e32 v108, v84, v180
	v_add_f32_e32 v180, v85, v108
	v_cvt_pk_bf16_f32 v108, v84, v85
	s_waitcnt lgkmcnt(4)
	v_mfma_f32_32x32x16_bf16 v[52:67], v[176:179], v[164:167], v[52:67]
	v_exp_f32_e32 v86, v86
	ds_read_b64_tr_b16 v[112:113], v190 offset:17408
	ds_read_b64_tr_b16 v[114:115], v190 offset:17920
	v_exp_f32_e32 v87, v87
	v_add_f32_e32 v109, v180, v86
	v_add_f32_e32 v172, v87, v109
	v_cvt_pk_bf16_f32 v109, v86, v87
	s_waitcnt lgkmcnt(4)
	v_mfma_f32_32x32x16_bf16 v[36:51], v[100:103], v[164:167], v[36:51]
	v_exp_f32_e32 v88, v88
	ds_read_b64_tr_b16 v[176:177], v190 offset:21504
	ds_read_b64_tr_b16 v[178:179], v190 offset:22016
	v_exp_f32_e32 v89, v89
	v_add_f32_e32 v100, v172, v88
	v_add_f32_e32 v172, v89, v100
	v_cvt_pk_bf16_f32 v110, v88, v89
	s_waitcnt lgkmcnt(4)
	v_mfma_f32_32x32x16_bf16 v[20:35], v[104:107], v[164:167], v[20:35]
	v_exp_f32_e32 v90, v90
	v_exp_f32_e32 v91, v91
	ds_read_b64_tr_b16 v[100:101], v190 offset:25600
	ds_read_b64_tr_b16 v[102:103], v190 offset:26112
	v_add_f32_e32 v104, v172, v90
	v_cvt_pk_bf16_f32 v111, v90, v91
	v_add_f32_e32 v172, v91, v104
	s_waitcnt lgkmcnt(4)
	v_mfma_f32_32x32x16_bf16 v[68:83], v[112:115], v[168:171], v[68:83]
	v_exp_f32_e32 v92, v92
	v_exp_f32_e32 v93, v93
	ds_read_b64_tr_b16 v[104:105], v190 offset:29696
	ds_read_b64_tr_b16 v[106:107], v190 offset:30208
	v_add_f32_e32 v164, v172, v92
	v_add_f32_e32 v180, v93, v164
	v_cvt_pk_bf16_f32 v112, v92, v93
	s_waitcnt lgkmcnt(4)
	v_mfma_f32_32x32x16_bf16 v[52:67], v[176:179], v[168:171], v[52:67]
	v_exp_f32_e32 v94, v94
	ds_read_b64_tr_b16 v[172:173], v190 offset:18432
	ds_read_b64_tr_b16 v[174:175], v190 offset:18944
	v_exp_f32_e32 v95, v95
	v_add_f32_e32 v165, v180, v94
	v_add_f32_e32 v166, v95, v165
	v_cvt_pk_bf16_f32 v113, v94, v95
	s_waitcnt lgkmcnt(4)
	v_mfma_f32_32x32x16_bf16 v[36:51], v[100:103], v[168:171], v[36:51]
	v_exp_f32_e32 v96, v96
	ds_read_b64_tr_b16 v[176:177], v190 offset:22528
	ds_read_b64_tr_b16 v[178:179], v190 offset:23040
	v_exp_f32_e32 v97, v97
	v_add_f32_e32 v100, v166, v96
	v_add_f32_e32 v100, v97, v100
	v_cvt_pk_bf16_f32 v114, v96, v97
	s_waitcnt lgkmcnt(4)
	v_mfma_f32_32x32x16_bf16 v[20:35], v[104:107], v[168:171], v[20:35]
	v_exp_f32_e32 v98, v98
	v_exp_f32_e32 v99, v99
	ds_read_b64_tr_b16 v[180:181], v190 offset:26624
	ds_read_b64_tr_b16 v[182:183], v190 offset:27136
	v_add_f32_e32 v100, v100, v98
	v_cvt_pk_bf16_f32 v115, v98, v99
	v_add_f32_e32 v100, v99, v100
	s_cmp_le_i32 s4, s13
	s_cbranch_scc1 .LBB0_405
; DI float max3f(float a, float b, float c) { float r; asm("v_max3_f32 %0, %1, %2, %3" : "=v"(r) : "v"(a), "v"(b), "v"(c)); return r; }
; #define SBAR() __builtin_amdgcn_sched_barrier(0)
; #define PIN(x) asm volatile("" : "+v"(x))
; #define LDV(j_) do { if ((j_) < 4 * NDB) { const lds_cptr a_ = vp + ((j_) % NDB) * 4096 + ((j_) / NDB) * 1024; const s16x4 lo_ = vtr(a_), hi_ = vtr(a_ + 512); \
;             vq[(j_) & 3] = (bf16x8){lo_[0], lo_[1], lo_[2], lo_[3], hi_[0], hi_[1], hi_[2], hi_[3]}; } } while (0)
; #define PVM(j_) o[(j_) % NDB] = MF(vq[(j_) & 3], pw[(j_) / NDB], o[(j_) % NDB])
; template <int KIND> DI void attn_unit(const Params& P, int b, int h, int qb, char* shm, float lam, bool dry = false) {
;     ...
;             LDV(11); PVM(8); rm = max3f(pb0[0], pb0[1], pb1[0]); rm2 = max3f(pb0[2], pb0[3], pb1[1]); PIN(rm); PIN(rm2); SBAR();
	ds_read2_b32 v[84:85], v192 offset1:1
	ds_read2_b32 v[86:87], v192 offset0:2 offset1:3
	ds_read2_b32 v[88:89], v192 offset0:8 offset1:9
	ds_read2_b32 v[90:91], v192 offset0:10 offset1:11
	ds_read2_b32 v[92:93], v192 offset0:16 offset1:17
	ds_read2_b32 v[94:95], v192 offset0:18 offset1:19
	ds_read2_b32 v[96:97], v192 offset0:24 offset1:25
	ds_read2_b32 v[98:99], v192 offset0:26 offset1:27
	ds_read2_b32 v[102:103], v192 offset0:32 offset1:33
	ds_read2_b32 v[104:105], v192 offset0:34 offset1:35
	ds_read2_b32 v[106:107], v192 offset0:40 offset1:41
	ds_read2_b32 v[164:165], v192 offset0:42 offset1:43
	s_waitcnt lgkmcnt(11)
	v_pk_add_f32 v[116:117], v[116:117], v[84:85]
	s_waitcnt lgkmcnt(5)
	v_pk_add_f32 v[128:129], v[128:129], v[96:97]
	v_pk_add_f32 v[126:127], v[126:127], v[94:95]
	v_pk_add_f32 v[124:125], v[124:125], v[92:93]
	ds_read2_b32 v[84:85], v192 offset0:48 offset1:49
	ds_read2_b32 v[92:93], v192 offset0:50 offset1:51
	ds_read2_b32 v[94:95], v192 offset0:56 offset1:57
	ds_read2_b32 v[96:97], v192 offset0:58 offset1:59
	s_waitcnt lgkmcnt(8)
	v_pk_add_f32 v[130:131], v[130:131], v[98:99]
	v_pk_add_f32 v[122:123], v[122:123], v[90:91]
	v_pk_add_f32 v[120:121], v[120:121], v[88:89]
	v_pk_add_f32 v[118:119], v[118:119], v[86:87]
	s_waitcnt lgkmcnt(7)
	v_pk_add_f32 v[132:133], v[132:133], v[102:103]
	s_waitcnt lgkmcnt(0)
	v_pk_add_f32 v[146:147], v[146:147], v[96:97]
	v_pk_add_f32 v[144:145], v[144:145], v[94:95]
	v_pk_add_f32 v[142:143], v[142:143], v[92:93]
	v_pk_add_f32 v[140:141], v[140:141], v[84:85]
	v_pk_add_f32 v[138:139], v[138:139], v[164:165]
	v_pk_add_f32 v[136:137], v[136:137], v[106:107]
	v_pk_add_f32 v[134:135], v[134:135], v[104:105]
.LBB0_405:
	s_waitcnt lgkmcnt(4)
	v_mfma_f32_32x32x16_bf16 v[68:83], v[172:175], v[108:111], v[68:83]
	s_cmp_lt_u32 s3, s7
	s_cbranch_scc1 .Lat1_nomask
	v_mov_b32_e32 v116, v245
	v_mov_b32_e32 v117, v245
	v_mov_b32_e32 v118, v245
	v_mov_b32_e32 v119, v245
	v_mov_b32_e32 v120, v245
	v_mov_b32_e32 v121, v245
	v_mov_b32_e32 v122, v245
	v_mov_b32_e32 v123, v245
	v_mov_b32_e32 v124, v245
	v_mov_b32_e32 v125, v245
	v_mov_b32_e32 v126, v245
	v_mov_b32_e32 v127, v245
	v_mov_b32_e32 v128, v245
	v_mov_b32_e32 v129, v245
	v_mov_b32_e32 v130, v245
	v_mov_b32_e32 v131, v245
	v_mov_b32_e32 v132, v245
	v_mov_b32_e32 v133, v245
	v_mov_b32_e32 v134, v245
	v_mov_b32_e32 v135, v245
	v_mov_b32_e32 v136, v245
	v_mov_b32_e32 v137, v245
	v_mov_b32_e32 v138, v245
	v_mov_b32_e32 v139, v245
	v_mov_b32_e32 v140, v245
	v_mov_b32_e32 v141, v245
	v_mov_b32_e32 v142, v245
	v_mov_b32_e32 v143, v245
	v_mov_b32_e32 v144, v245
	v_mov_b32_e32 v145, v245
	v_mov_b32_e32 v146, v245
	v_mov_b32_e32 v147, v245
; template <int KIND> DI void attn_unit(const Params& P, int b, int h, int qb, char* shm, float lam, bool dry = false) {
;     ...
;             LDV(11); PVM(8); rm = max3f(pb0[0], pb0[1], pb1[0]); rm2 = max3f(pb0[2], pb0[3], pb1[1]); PIN(rm); PIN(rm2); SBAR();
;             LDV(12); PVM(9); rm = max3f(rm, pb1[2], pb1[3]); rm2 = max3f(rm2, pb0[4], pb0[5]); PIN(rm); PIN(rm2); SBAR();
;             LDV(13); PVM(10); rm = max3f(rm, pb0[6], pb0[7]); rm2 = max3f(rm2, pb1[4], pb1[5]); PIN(rm); PIN(rm2); SBAR();
;             LDV(14); PVM(11); rm = max3f(rm, pb1[6], pb1[7]); rm2 = max3f(rm2, pb0[8], pb0[9]); PIN(rm); PIN(rm2); SBAR();
;             LDV(15); PVM(12); rm = max3f(rm, pb0[10], pb0[11]); rm2 = max3f(rm2, pb1[8], pb1[9]); PIN(rm); PIN(rm2); SBAR();
;             PVM(13); rm = max3f(rm, pb1[10], pb1[11]); rm2 = max3f(rm2, pb0[12], pb0[13]); PIN(rm); PIN(rm2); SBAR();
;             PVM(14); rm = max3f(rm, pb0[14], pb0[15]); rm2 = max3f(rm2, pb1[12], pb1[13]); PIN(rm); PIN(rm2); SBAR();
;             PVM(15); rm = max3f(rm, pb1[14], pb1[15]); PIN(rm); SBAR();
;         } else {
;             LDV(7); PVM(4); rm = max3f(pb0[0], pb0[1], pb1[0]); rm2 = max3f(pb0[2], pb0[3], pb1[1]); rm = max3f(rm, pb1[2], pb1[3]); rm2 = max3f(rm2, pb0[4], pb0[5]); PIN(rm); PIN(rm2); SBAR();
;             PVM(5); rm = max3f(rm, pb0[6], pb0[7]); rm2 = max3f(rm2, pb1[4], pb1[5]); rm = max3f(rm, pb1[6], pb1[7]); rm2 = max3f(rm2, pb0[8], pb0[9]); PIN(rm); PIN(rm2); SBAR();
;             PVM(6); rm = max3f(rm, pb0[10], pb0[11]); rm2 = max3f(rm2, pb1[8], pb1[9]); rm = max3f(rm, pb1[10], pb1[11]); rm2 = max3f(rm2, pb0[12], pb0[13]); PIN(rm); PIN(rm2); SBAR();
;             PVM(7); rm = max3f(rm, pb0[14], pb0[15]); rm2 = max3f(rm2, pb1[12], pb1[13]); rm = max3f(rm, pb1[14], pb1[15]); PIN(rm); PIN(rm2); SBAR();
;         }
;     ...
;         rm = swapmax(max3f(rm, rm2, rm2));
;         if (KIND == 2) {
;             const u32x2 kx = *(const LAS u32x2*)(shm3 + sc + 32768);
;             const float xk0 = __uint_as_float(kx.x << 16) + __uint_as_float(kx.x & 0xffff0000u) + __uint_as_float(kx.y << 16);
;             const float ltot = swapsum(lsum);
;             const bool ok = (qkmax + cb + xk0) < (mhat + __builtin_amdgcn_logf(ltot) - 54.0f);
;             const bool allok = __all(ok) && !(ATT_TILE(i) > wt_hi);
;             if (lane == 0) vote[8 * (i & 3) + wid] = allok ? 1u : 0u;
;         }
.Lat1_nomask:
	v_add_f32_e32 v197, v197, v100
	ds_read_b64_tr_b16 v[84:85], v190 offset:30720
	ds_read_b64_tr_b16 v[86:87], v190 offset:31232
	v_max3_f32 v100, v116, v117, v132
	v_max3_f32 v101, v118, v119, v133
	s_waitcnt lgkmcnt(4)
	v_mfma_f32_32x32x16_bf16 v[52:67], v[176:179], v[108:111], v[52:67]
	ds_read_b64_tr_b16 v[88:89], v190 offset:19456
	ds_read_b64_tr_b16 v[90:91], v190 offset:19968
	v_max3_f32 v100, v100, v134, v135
	v_max3_f32 v101, v101, v120, v121
	s_waitcnt lgkmcnt(4)
	v_mfma_f32_32x32x16_bf16 v[36:51], v[180:183], v[108:111], v[36:51]
	ds_read_b64_tr_b16 v[92:93], v190 offset:23552
	ds_read_b64_tr_b16 v[94:95], v190 offset:24064
	v_max3_f32 v100, v100, v122, v123
	v_max3_f32 v101, v101, v136, v137
	s_waitcnt lgkmcnt(4)
	v_mfma_f32_32x32x16_bf16 v[20:35], v[84:87], v[108:111], v[20:35]
	ds_read_b64_tr_b16 v[96:97], v190 offset:27648
	ds_read_b64_tr_b16 v[98:99], v190 offset:28160
	v_max3_f32 v100, v100, v138, v139
	v_max3_f32 v101, v101, v124, v125
	s_waitcnt lgkmcnt(4)
	v_mfma_f32_32x32x16_bf16 v[68:83], v[88:91], v[112:115], v[68:83]
	ds_read_b64_tr_b16 v[84:85], v190 offset:31744
	ds_read_b64_tr_b16 v[86:87], v190 offset:32256
	v_max3_f32 v100, v100, v126, v127
	v_max3_f32 v101, v101, v140, v141
	s_waitcnt lgkmcnt(4)
	v_mfma_f32_32x32x16_bf16 v[52:67], v[92:95], v[112:115], v[52:67]
	v_max3_f32 v100, v100, v142, v143
	v_max3_f32 v101, v101, v128, v129
	s_waitcnt lgkmcnt(2)
	v_mfma_f32_32x32x16_bf16 v[36:51], v[96:99], v[112:115], v[36:51]
	v_max3_f32 v100, v100, v130, v131
	v_max3_f32 v101, v101, v144, v145
	s_waitcnt lgkmcnt(0)
	v_mfma_f32_32x32x16_bf16 v[20:35], v[84:87], v[112:115], v[20:35]
	v_max3_f32 v100, v100, v146, v147
	v_max3_f32 v100, v100, v101, v101
	s_add_i32 s3, s3, 1
	v_mov_b32_e32 v101, v100
	s_cmp_ge_u32 s3, s18
	s_nop 0
	v_permlane32_swap_b32_e32 v100, v101
	s_cbranch_scc1 .LBB0_408
	v_max_f32_e32 v100, v100, v100
	v_max_f32_e32 v101, v101, v101
	v_max_f32_e32 v100, v100, v101
	v_cmp_lt_f32_e32 vcc, s88, v100
	s_cbranch_vccz .LBB0_408
	v_max_f32_e32 v100, v100, v100
	v_max_f32_e32 v101, 0, v100
	v_exp_f32_e64 v100, -v101
	v_sub_f32_e32 v131, v131, v101
	v_sub_f32_e32 v130, v130, v101
	v_sub_f32_e32 v129, v129, v101
	v_pk_mul_f32 v[82:83], v[82:83], v[100:101] op_sel_hi:[1,0]
	v_pk_mul_f32 v[80:81], v[80:81], v[100:101] op_sel_hi:[1,0]
	v_pk_mul_f32 v[78:79], v[78:79], v[100:101] op_sel_hi:[1,0]
	v_pk_mul_f32 v[76:77], v[76:77], v[100:101] op_sel_hi:[1,0]
	v_pk_mul_f32 v[74:75], v[74:75], v[100:101] op_sel_hi:[1,0]
	v_pk_mul_f32 v[72:73], v[72:73], v[100:101] op_sel_hi:[1,0]
	v_pk_mul_f32 v[70:71], v[70:71], v[100:101] op_sel_hi:[1,0]
	v_pk_mul_f32 v[68:69], v[68:69], v[100:101] op_sel_hi:[1,0]
	v_pk_mul_f32 v[66:67], v[66:67], v[100:101] op_sel_hi:[1,0]
	v_pk_mul_f32 v[64:65], v[64:65], v[100:101] op_sel_hi:[1,0]
	v_pk_mul_f32 v[62:63], v[62:63], v[100:101] op_sel_hi:[1,0]
	v_pk_mul_f32 v[60:61], v[60:61], v[100:101] op_sel_hi:[1,0]
	v_pk_mul_f32 v[58:59], v[58:59], v[100:101] op_sel_hi:[1,0]
	v_pk_mul_f32 v[56:57], v[56:57], v[100:101] op_sel_hi:[1,0]
	v_pk_mul_f32 v[54:55], v[54:55], v[100:101] op_sel_hi:[1,0]
	v_pk_mul_f32 v[52:53], v[52:53], v[100:101] op_sel_hi:[1,0]
	v_pk_mul_f32 v[50:51], v[50:51], v[100:101] op_sel_hi:[1,0]
	v_pk_mul_f32 v[48:49], v[48:49], v[100:101] op_sel_hi:[1,0]
	v_pk_mul_f32 v[46:47], v[46:47], v[100:101] op_sel_hi:[1,0]
	v_pk_mul_f32 v[44:45], v[44:45], v[100:101] op_sel_hi:[1,0]
	v_pk_mul_f32 v[42:43], v[42:43], v[100:101] op_sel_hi:[1,0]
	v_pk_mul_f32 v[40:41], v[40:41], v[100:101] op_sel_hi:[1,0]
	v_pk_mul_f32 v[38:39], v[38:39], v[100:101] op_sel_hi:[1,0]
	v_pk_mul_f32 v[36:37], v[36:37], v[100:101] op_sel_hi:[1,0]
	v_pk_mul_f32 v[34:35], v[34:35], v[100:101] op_sel_hi:[1,0]
	v_pk_mul_f32 v[32:33], v[32:33], v[100:101] op_sel_hi:[1,0]
	v_pk_mul_f32 v[30:31], v[30:31], v[100:101] op_sel_hi:[1,0]
	v_pk_mul_f32 v[28:29], v[28:29], v[100:101] op_sel_hi:[1,0]
	v_pk_mul_f32 v[26:27], v[26:27], v[100:101] op_sel_hi:[1,0]
	v_pk_mul_f32 v[24:25], v[24:25], v[100:101] op_sel_hi:[1,0]
	v_pk_mul_f32 v[22:23], v[22:23], v[100:101] op_sel_hi:[1,0]
	v_pk_mul_f32 v[20:21], v[20:21], v[100:101] op_sel_hi:[1,0]
	v_sub_f32_e32 v128, v128, v101
	v_sub_f32_e32 v127, v127, v101
	v_sub_f32_e32 v126, v126, v101
	v_sub_f32_e32 v125, v125, v101
	v_sub_f32_e32 v124, v124, v101
	v_sub_f32_e32 v123, v123, v101
	v_sub_f32_e32 v122, v122, v101
	v_sub_f32_e32 v121, v121, v101
	v_sub_f32_e32 v120, v120, v101
	v_sub_f32_e32 v119, v119, v101
	v_sub_f32_e32 v118, v118, v101
	v_sub_f32_e32 v117, v117, v101
	v_sub_f32_e32 v116, v116, v101
	v_sub_f32_e32 v147, v147, v101
	v_sub_f32_e32 v146, v146, v101
	v_sub_f32_e32 v145, v145, v101
	v_sub_f32_e32 v144, v144, v101
	v_sub_f32_e32 v143, v143, v101
	v_sub_f32_e32 v142, v142, v101
	v_sub_f32_e32 v141, v141, v101
	v_sub_f32_e32 v140, v140, v101
	v_sub_f32_e32 v139, v139, v101
	v_sub_f32_e32 v138, v138, v101
	v_sub_f32_e32 v137, v137, v101
	v_sub_f32_e32 v136, v136, v101
	v_sub_f32_e32 v135, v135, v101
	v_sub_f32_e32 v134, v134, v101
	v_sub_f32_e32 v133, v133, v101
	v_sub_f32_e32 v132, v132, v101
	v_sub_f32_e32 v19, v19, v101
	v_sub_f32_e32 v18, v18, v101
	v_sub_f32_e32 v17, v17, v101
	v_sub_f32_e32 v16, v16, v101
	v_sub_f32_e32 v15, v15, v101
	v_sub_f32_e32 v14, v14, v101
	v_sub_f32_e32 v13, v13, v101
	v_sub_f32_e32 v12, v12, v101
	v_sub_f32_e32 v11, v11, v101
	v_sub_f32_e32 v10, v10, v101
	v_sub_f32_e32 v9, v9, v101
	v_sub_f32_e32 v8, v8, v101
	v_sub_f32_e32 v7, v7, v101
	v_sub_f32_e32 v6, v6, v101
	v_sub_f32_e32 v5, v5, v101
	v_sub_f32_e32 v4, v4, v101
	v_mul_f32_e32 v197, v197, v100

; #define SBAR() __builtin_amdgcn_sched_barrier(0)
; #define PIN(x) asm volatile("" : "+v"(x))
; #define MF(a_, b_, c_) __builtin_amdgcn_mfma_f32_32x32x16_bf16(a_, b_, c_, 0, 0, 0)
; #define PVM(j_) o[(j_) % NDB] = MF(vq[(j_) & 3], pw[(j_) / NDB], o[(j_) % NDB])
; template <int KIND> DI void attn_unit(const Params& P, int b, int h, int qb, char* shm, float lam, bool dry = false) {
;     ...
;         ATT_KLD(sn, 0); ATT_XLD(sn);
;         SBAR();
;     ...
;         G1(pb0 = MF(kf[0], qr[0], negm), 0, w0, 0);  G1(pb1 = MF(kf[1], qr[0], negm), 2, w0, 1);
;         G1(pb0 = MF(kf[2], qr[1], pb0), 4, w0, 2);   G1(pb1 = MF(kf[3], qr[1], pb1), 6, w0, 3);
;         ATT_KLD(sn, 1);
;         SBAR();
;         G1(pb0 = MF(kf[0], qr[2], pb0), 8, w1, 0);   G1(pb1 = MF(kf[1], qr[2], pb1), 10, w1, 1);
;         LDV(0); SBAR();
;         G1(pb0 = MF(kf[2], qr[3], pb0), 12, w1, 2);
;         LDV(1); SBAR();
;         G1(pb1 = MF(kf[3], qr[3], pb1), 14, w1, 3);
;         LDV(2); SBAR();
;     ...
;         if (KIND == 2) { pb0 = MF(x0, ones, pb0); pb1 = MF(x1, ones, pb1); }
;         pw[0] = __builtin_bit_cast(bf16x8, w0); pw[1] = __builtin_bit_cast(bf16x8, w1);
;     ...
;         if (NDB == 4) {
;             LDV(3); PVM(0); E4(0, w0, 0); PIN(pa1); PIN(sacc); PIN(w0); SBAR();
;             LDV(4); PVM(1); E4(2, w0, 1); PIN(pa1); PIN(sacc); PIN(w0); SBAR();
;             LDV(5); PVM(2); E4(4, w0, 2); PIN(pa1); PIN(sacc); PIN(w0); SBAR();
;             LDV(6); PVM(3); E4(6, w0, 3); PIN(pa1); PIN(sacc); PIN(w0); SBAR();
;             LDV(7); PVM(4); E4(8, w1, 0); PIN(pa1); PIN(sacc); PIN(w1); SBAR();
;             LDV(8); PVM(5); E4(10, w1, 1); PIN(pa1); PIN(sacc); PIN(w1); SBAR();
;             LDV(9); PVM(6); E4(12, w1, 2); PIN(pa1); PIN(sacc); PIN(w1); SBAR();
;             LDV(10); PVM(7); E4(14, w1, 3); PIN(pa1); PIN(sacc); PIN(w1); SBAR();
;         } else {
;             LDV(3); PVM(0); E4(0, w0, 0); E4(2, w0, 1); PIN(pa1); PIN(sacc); PIN(w0); SBAR();
;             LDV(4); PVM(1); E4(4, w0, 2); E4(6, w0, 3); PIN(pa1); PIN(sacc); PIN(w0); SBAR();
;             LDV(5); PVM(2); E4(8, w1, 0); E4(10, w1, 1); PIN(pa1); PIN(sacc); PIN(w1); SBAR();
;             LDV(6); PVM(3); E4(12, w1, 2); E4(14, w1, 3); PIN(pa1); PIN(sacc); PIN(w1); SBAR();
;         }
;     ...
;         pw[2] = __builtin_bit_cast(bf16x8, w0); pw[3] = __builtin_bit_cast(bf16x8, w1);
;         lsum += sacc;
.Lat2_403:
	s_add_i32 s0, s5, 0x8400
	s_cmp_lg_u32 s5, 0x18c00
	s_cselect_b32 s0, s0, 0
	v_add_u32_e32 v168, s0, v193
	ds_read_b128 v[84:87], v168
	ds_read_b128 v[172:175], v168 offset:512
	ds_read_b128 v[176:179], v168 offset:2048
	ds_read_b128 v[180:183], v168 offset:2560
	v_add_u32_e32 v190, s5, v196
	s_waitcnt lgkmcnt(3)
	v_mfma_f32_32x32x16_bf16 v[100:115], v[84:87], v[160:163], v[4:19]
	v_exp_f32_e32 v116, v116
	v_exp_f32_e32 v117, v117
	v_add_f32_e32 v84, 0, v116
	v_add_f32_e32 v191, v117, v84
	v_cvt_pk_bf16_f32 v164, v116, v117
	s_waitcnt lgkmcnt(2)
	v_mfma_f32_32x32x16_bf16 v[84:99], v[172:175], v[160:163], v[4:19]
	v_exp_f32_e32 v118, v118
	v_exp_f32_e32 v119, v119
	v_add_f32_e32 v165, v191, v118
	v_add_f32_e32 v172, v119, v165
	v_cvt_pk_bf16_f32 v165, v118, v119
	s_waitcnt lgkmcnt(1)
	v_mfma_f32_32x32x16_bf16 v[100:115], v[176:179], v[156:159], v[100:115]
	v_exp_f32_e32 v120, v120
	v_exp_f32_e32 v121, v121
	v_add_f32_e32 v166, v172, v120
	v_add_f32_e32 v172, v121, v166
	v_cvt_pk_bf16_f32 v166, v120, v121
	s_waitcnt lgkmcnt(0)
	v_mfma_f32_32x32x16_bf16 v[84:99], v[180:183], v[156:159], v[84:99]
	v_exp_f32_e32 v122, v122
	v_exp_f32_e32 v123, v123
	v_add_f32_e32 v167, v172, v122
	v_add_f32_e32 v191, v123, v167
	v_cvt_pk_bf16_f32 v167, v122, v123
	ds_read_b128 v[172:175], v168 offset:4096
	ds_read_b128 v[176:179], v168 offset:4608
	ds_read_b128 v[180:183], v168 offset:6144
	ds_read_b128 v[214:217], v168 offset:6656
	s_waitcnt lgkmcnt(3)
	v_mfma_f32_32x32x16_bf16 v[100:115], v[172:175], v[152:155], v[100:115]
	v_exp_f32_e32 v124, v124
	v_exp_f32_e32 v125, v125
	v_add_f32_e32 v168, v191, v124
	v_add_f32_e32 v172, v125, v168
	v_cvt_pk_bf16_f32 v168, v124, v125
	s_waitcnt lgkmcnt(2)
	v_mfma_f32_32x32x16_bf16 v[84:99], v[176:179], v[152:155], v[84:99]
	v_exp_f32_e32 v126, v126
	v_exp_f32_e32 v127, v127
	v_add_f32_e32 v169, v172, v126
	v_add_f32_e32 v176, v127, v169
	v_cvt_pk_bf16_f32 v169, v126, v127
	ds_read_b64_tr_b16 v[172:173], v190 offset:16384
	ds_read_b64_tr_b16 v[174:175], v190 offset:16896
	s_waitcnt lgkmcnt(3)
	v_mfma_f32_32x32x16_bf16 v[100:115], v[180:183], v[148:151], v[100:115]
	v_exp_f32_e32 v128, v128
	v_exp_f32_e32 v129, v129
	v_add_f32_e32 v170, v176, v128
	v_add_f32_e32 v180, v129, v170
	v_cvt_pk_bf16_f32 v170, v128, v129
	ds_read_b64_tr_b16 v[176:177], v190 offset:20480
	ds_read_b64_tr_b16 v[178:179], v190 offset:20992
	s_waitcnt lgkmcnt(4)
	v_mfma_f32_32x32x16_bf16 v[84:99], v[214:217], v[148:151], v[84:99]
	v_exp_f32_e32 v130, v130
	v_exp_f32_e32 v131, v131
	v_add_f32_e32 v171, v180, v130
	v_add_f32_e32 v180, v131, v171
	v_cvt_pk_bf16_f32 v171, v130, v131
	ds_read_b64_tr_b16 v[116:117], v190 offset:24576
	ds_read_b64_tr_b16 v[118:119], v190 offset:25088
	s_waitcnt lgkmcnt(4)
	v_mfma_f32_32x32x16_bf16 v[68:83], v[172:175], v[164:167], v[68:83]
	v_exp_f32_e32 v132, v132
	v_exp_f32_e32 v133, v133
	ds_read_b64_tr_b16 v[120:121], v190 offset:28672
	ds_read_b64_tr_b16 v[122:123], v190 offset:29184
	v_add_f32_e32 v124, v132, v180
	v_add_f32_e32 v180, v133, v124
	v_cvt_pk_bf16_f32 v124, v132, v133
	s_waitcnt lgkmcnt(4)
	v_mfma_f32_32x32x16_bf16 v[52:67], v[176:179], v[164:167], v[52:67]
	v_exp_f32_e32 v134, v134
	ds_read_b64_tr_b16 v[128:129], v190 offset:17408
	ds_read_b64_tr_b16 v[130:131], v190 offset:17920
	v_exp_f32_e32 v135, v135
	v_add_f32_e32 v125, v180, v134
	v_add_f32_e32 v172, v135, v125
	v_cvt_pk_bf16_f32 v125, v134, v135
	s_waitcnt lgkmcnt(4)
	v_mfma_f32_32x32x16_bf16 v[36:51], v[116:119], v[164:167], v[36:51]
	v_exp_f32_e32 v136, v136
	ds_read_b64_tr_b16 v[176:177], v190 offset:21504
	ds_read_b64_tr_b16 v[178:179], v190 offset:22016
	v_exp_f32_e32 v137, v137
	v_add_f32_e32 v116, v172, v136
	v_add_f32_e32 v172, v137, v116
	v_cvt_pk_bf16_f32 v126, v136, v137
	s_waitcnt lgkmcnt(4)
	v_mfma_f32_32x32x16_bf16 v[20:35], v[120:123], v[164:167], v[20:35]
	v_exp_f32_e32 v138, v138
	v_exp_f32_e32 v139, v139
	ds_read_b64_tr_b16 v[116:117], v190 offset:25600
	ds_read_b64_tr_b16 v[118:119], v190 offset:26112
	v_add_f32_e32 v120, v172, v138
	v_cvt_pk_bf16_f32 v127, v138, v139
	v_add_f32_e32 v172, v139, v120
	s_waitcnt lgkmcnt(4)
	v_mfma_f32_32x32x16_bf16 v[68:83], v[128:131], v[168:171], v[68:83]
	v_exp_f32_e32 v140, v140
	v_exp_f32_e32 v141, v141
	ds_read_b64_tr_b16 v[120:121], v190 offset:29696
	ds_read_b64_tr_b16 v[122:123], v190 offset:30208
	v_add_f32_e32 v164, v172, v140
	v_add_f32_e32 v180, v141, v164
	v_cvt_pk_bf16_f32 v128, v140, v141
	s_waitcnt lgkmcnt(4)
	v_mfma_f32_32x32x16_bf16 v[52:67], v[176:179], v[168:171], v[52:67]
	v_exp_f32_e32 v142, v142
	ds_read_b64_tr_b16 v[172:173], v190 offset:18432
	ds_read_b64_tr_b16 v[174:175], v190 offset:18944
	v_exp_f32_e32 v143, v143
	v_add_f32_e32 v165, v180, v142
	v_add_f32_e32 v166, v143, v165
	v_cvt_pk_bf16_f32 v129, v142, v143
	s_waitcnt lgkmcnt(4)
	v_mfma_f32_32x32x16_bf16 v[36:51], v[116:119], v[168:171], v[36:51]
	v_exp_f32_e32 v144, v144
	ds_read_b64_tr_b16 v[176:177], v190 offset:22528
	ds_read_b64_tr_b16 v[178:179], v190 offset:23040
	v_exp_f32_e32 v145, v145
	v_add_f32_e32 v116, v166, v144
	v_add_f32_e32 v116, v145, v116
	v_cvt_pk_bf16_f32 v130, v144, v145
	s_waitcnt lgkmcnt(4)
	v_mfma_f32_32x32x16_bf16 v[20:35], v[120:123], v[168:171], v[20:35]
	v_exp_f32_e32 v146, v146
	v_exp_f32_e32 v147, v147
	ds_read_b64_tr_b16 v[180:181], v190 offset:26624
	ds_read_b64_tr_b16 v[182:183], v190 offset:27136
	v_add_f32_e32 v116, v116, v146
	v_cvt_pk_bf16_f32 v131, v146, v147
	v_add_f32_e32 v116, v147, v116
	s_cmp_le_i32 s4, s13
	s_cbranch_scc1 .Lat2_405
; DI float max3f(float a, float b, float c) { float r; asm("v_max3_f32 %0, %1, %2, %3" : "=v"(r) : "v"(a), "v"(b), "v"(c)); return r; }
; #define SBAR() __builtin_amdgcn_sched_barrier(0)
; #define PIN(x) asm volatile("" : "+v"(x))
; #define LDV(j_) do { if ((j_) < 4 * NDB) { const lds_cptr a_ = vp + ((j_) % NDB) * 4096 + ((j_) / NDB) * 1024; const s16x4 lo_ = vtr(a_), hi_ = vtr(a_ + 512); \
;             vq[(j_) & 3] = (bf16x8){lo_[0], lo_[1], lo_[2], lo_[3], hi_[0], hi_[1], hi_[2], hi_[3]}; } } while (0)
; #define PVM(j_) o[(j_) % NDB] = MF(vq[(j_) & 3], pw[(j_) / NDB], o[(j_) % NDB])
; template <int KIND> DI void attn_unit(const Params& P, int b, int h, int qb, char* shm, float lam, bool dry = false) {
;     ...
;             LDV(11); PVM(8); rm = max3f(pb0[0], pb0[1], pb1[0]); rm2 = max3f(pb0[2], pb0[3], pb1[1]); PIN(rm); PIN(rm2); SBAR();
	ds_read2_b32 v[132:133], v192 offset1:1
	ds_read2_b32 v[134:135], v192 offset0:2 offset1:3
	ds_read2_b32 v[136:137], v192 offset0:8 offset1:9
	ds_read2_b32 v[138:139], v192 offset0:10 offset1:11
	ds_read2_b32 v[140:141], v192 offset0:16 offset1:17
	ds_read2_b32 v[142:143], v192 offset0:18 offset1:19
	ds_read2_b32 v[144:145], v192 offset0:24 offset1:25
	ds_read2_b32 v[146:147], v192 offset0:26 offset1:27
	ds_read2_b32 v[118:119], v192 offset0:32 offset1:33
	ds_read2_b32 v[120:121], v192 offset0:34 offset1:35
	ds_read2_b32 v[122:123], v192 offset0:40 offset1:41
	ds_read2_b32 v[164:165], v192 offset0:42 offset1:43
	s_waitcnt lgkmcnt(11)
	v_pk_add_f32 v[100:101], v[100:101], v[132:133]
	s_waitcnt lgkmcnt(5)
	v_pk_add_f32 v[112:113], v[112:113], v[144:145]
	v_pk_add_f32 v[110:111], v[110:111], v[142:143]
	v_pk_add_f32 v[108:109], v[108:109], v[140:141]
	ds_read2_b32 v[132:133], v192 offset0:48 offset1:49
	ds_read2_b32 v[140:141], v192 offset0:50 offset1:51
	ds_read2_b32 v[142:143], v192 offset0:56 offset1:57
	ds_read2_b32 v[144:145], v192 offset0:58 offset1:59
	s_waitcnt lgkmcnt(8)
	v_pk_add_f32 v[114:115], v[114:115], v[146:147]
	v_pk_add_f32 v[106:107], v[106:107], v[138:139]
	v_pk_add_f32 v[104:105], v[104:105], v[136:137]
	v_pk_add_f32 v[102:103], v[102:103], v[134:135]
	s_waitcnt lgkmcnt(7)
	v_pk_add_f32 v[84:85], v[84:85], v[118:119]
	s_waitcnt lgkmcnt(0)
	v_pk_add_f32 v[98:99], v[98:99], v[144:145]
	v_pk_add_f32 v[96:97], v[96:97], v[142:143]
	v_pk_add_f32 v[94:95], v[94:95], v[140:141]
	v_pk_add_f32 v[92:93], v[92:93], v[132:133]
	v_pk_add_f32 v[90:91], v[90:91], v[164:165]
	v_pk_add_f32 v[88:89], v[88:89], v[122:123]
	v_pk_add_f32 v[86:87], v[86:87], v[120:121]
.Lat2_405:
	s_waitcnt lgkmcnt(4)
	v_mfma_f32_32x32x16_bf16 v[68:83], v[172:175], v[124:127], v[68:83]
	s_cmp_lt_u32 s3, s7
	s_cbranch_scc1 .Lat2_nomask
	v_mov_b32_e32 v100, v245
	v_mov_b32_e32 v101, v245
	v_mov_b32_e32 v102, v245
	v_mov_b32_e32 v103, v245
	v_mov_b32_e32 v104, v245
	v_mov_b32_e32 v105, v245
	v_mov_b32_e32 v106, v245
	v_mov_b32_e32 v107, v245
	v_mov_b32_e32 v108, v245
	v_mov_b32_e32 v109, v245
	v_mov_b32_e32 v110, v245
	v_mov_b32_e32 v111, v245
	v_mov_b32_e32 v112, v245
	v_mov_b32_e32 v113, v245
	v_mov_b32_e32 v114, v245
	v_mov_b32_e32 v115, v245
	v_mov_b32_e32 v84, v245
	v_mov_b32_e32 v85, v245
	v_mov_b32_e32 v86, v245
	v_mov_b32_e32 v87, v245
	v_mov_b32_e32 v88, v245
	v_mov_b32_e32 v89, v245
	v_mov_b32_e32 v90, v245
	v_mov_b32_e32 v91, v245
	v_mov_b32_e32 v92, v245
	v_mov_b32_e32 v93, v245
	v_mov_b32_e32 v94, v245
	v_mov_b32_e32 v95, v245
	v_mov_b32_e32 v96, v245
	v_mov_b32_e32 v97, v245
	v_mov_b32_e32 v98, v245
	v_mov_b32_e32 v99, v245
; template <int KIND> DI void attn_unit(const Params& P, int b, int h, int qb, char* shm, float lam, bool dry = false) {
;     ...
;             LDV(11); PVM(8); rm = max3f(pb0[0], pb0[1], pb1[0]); rm2 = max3f(pb0[2], pb0[3], pb1[1]); PIN(rm); PIN(rm2); SBAR();
;             LDV(12); PVM(9); rm = max3f(rm, pb1[2], pb1[3]); rm2 = max3f(rm2, pb0[4], pb0[5]); PIN(rm); PIN(rm2); SBAR();
;             LDV(13); PVM(10); rm = max3f(rm, pb0[6], pb0[7]); rm2 = max3f(rm2, pb1[4], pb1[5]); PIN(rm); PIN(rm2); SBAR();
;             LDV(14); PVM(11); rm = max3f(rm, pb1[6], pb1[7]); rm2 = max3f(rm2, pb0[8], pb0[9]); PIN(rm); PIN(rm2); SBAR();
;             LDV(15); PVM(12); rm = max3f(rm, pb0[10], pb0[11]); rm2 = max3f(rm2, pb1[8], pb1[9]); PIN(rm); PIN(rm2); SBAR();
;             PVM(13); rm = max3f(rm, pb1[10], pb1[11]); rm2 = max3f(rm2, pb0[12], pb0[13]); PIN(rm); PIN(rm2); SBAR();
;             PVM(14); rm = max3f(rm, pb0[14], pb0[15]); rm2 = max3f(rm2, pb1[12], pb1[13]); PIN(rm); PIN(rm2); SBAR();
;             PVM(15); rm = max3f(rm, pb1[14], pb1[15]); PIN(rm); SBAR();
;         } else {
;             LDV(7); PVM(4); rm = max3f(pb0[0], pb0[1], pb1[0]); rm2 = max3f(pb0[2], pb0[3], pb1[1]); rm = max3f(rm, pb1[2], pb1[3]); rm2 = max3f(rm2, pb0[4], pb0[5]); PIN(rm); PIN(rm2); SBAR();
;             PVM(5); rm = max3f(rm, pb0[6], pb0[7]); rm2 = max3f(rm2, pb1[4], pb1[5]); rm = max3f(rm, pb1[6], pb1[7]); rm2 = max3f(rm2, pb0[8], pb0[9]); PIN(rm); PIN(rm2); SBAR();
;             PVM(6); rm = max3f(rm, pb0[10], pb0[11]); rm2 = max3f(rm2, pb1[8], pb1[9]); rm = max3f(rm, pb1[10], pb1[11]); rm2 = max3f(rm2, pb0[12], pb0[13]); PIN(rm); PIN(rm2); SBAR();
;             PVM(7); rm = max3f(rm, pb0[14], pb0[15]); rm2 = max3f(rm2, pb1[12], pb1[13]); rm = max3f(rm, pb1[14], pb1[15]); PIN(rm); PIN(rm2); SBAR();
;         }
;     ...
;         rm = swapmax(max3f(rm, rm2, rm2));
;         if (KIND == 2) {
;             const u32x2 kx = *(const LAS u32x2*)(shm3 + sc + 32768);
;             const float xk0 = __uint_as_float(kx.x << 16) + __uint_as_float(kx.x & 0xffff0000u) + __uint_as_float(kx.y << 16);
;             const float ltot = swapsum(lsum);
;             const bool ok = (qkmax + cb + xk0) < (mhat + __builtin_amdgcn_logf(ltot) - 54.0f);
;             const bool allok = __all(ok) && !(ATT_TILE(i) > wt_hi);
;             if (lane == 0) vote[8 * (i & 3) + wid] = allok ? 1u : 0u;
;         }
.Lat2_nomask:
	v_add_f32_e32 v197, v197, v116
	ds_read_b64_tr_b16 v[132:133], v190 offset:30720
	ds_read_b64_tr_b16 v[134:135], v190 offset:31232
	v_max3_f32 v116, v100, v101, v84
	v_max3_f32 v117, v102, v103, v85
	s_waitcnt lgkmcnt(4)
	v_mfma_f32_32x32x16_bf16 v[52:67], v[176:179], v[124:127], v[52:67]
	ds_read_b64_tr_b16 v[136:137], v190 offset:19456
	ds_read_b64_tr_b16 v[138:139], v190 offset:19968
	v_max3_f32 v116, v116, v86, v87
	v_max3_f32 v117, v117, v104, v105
	s_waitcnt lgkmcnt(4)
	v_mfma_f32_32x32x16_bf16 v[36:51], v[180:183], v[124:127], v[36:51]
	ds_read_b64_tr_b16 v[140:141], v190 offset:23552
	ds_read_b64_tr_b16 v[142:143], v190 offset:24064
	v_max3_f32 v116, v116, v106, v107
	v_max3_f32 v117, v117, v88, v89
	s_waitcnt lgkmcnt(4)
	v_mfma_f32_32x32x16_bf16 v[20:35], v[132:135], v[124:127], v[20:35]
	ds_read_b64_tr_b16 v[144:145], v190 offset:27648
	ds_read_b64_tr_b16 v[146:147], v190 offset:28160
	v_max3_f32 v116, v116, v90, v91
	v_max3_f32 v117, v117, v108, v109
	s_waitcnt lgkmcnt(4)
	v_mfma_f32_32x32x16_bf16 v[68:83], v[136:139], v[128:131], v[68:83]
	ds_read_b64_tr_b16 v[132:133], v190 offset:31744
	ds_read_b64_tr_b16 v[134:135], v190 offset:32256
	v_max3_f32 v116, v116, v110, v111
	v_max3_f32 v117, v117, v92, v93
	s_waitcnt lgkmcnt(4)
	v_mfma_f32_32x32x16_bf16 v[52:67], v[140:143], v[128:131], v[52:67]
	v_max3_f32 v116, v116, v94, v95
	v_max3_f32 v117, v117, v112, v113
	s_waitcnt lgkmcnt(2)
	v_mfma_f32_32x32x16_bf16 v[36:51], v[144:147], v[128:131], v[36:51]
	v_max3_f32 v116, v116, v114, v115
	v_max3_f32 v117, v117, v96, v97
	s_waitcnt lgkmcnt(0)
	v_mfma_f32_32x32x16_bf16 v[20:35], v[132:135], v[128:131], v[20:35]
	v_max3_f32 v116, v116, v98, v99
	v_max3_f32 v116, v116, v117, v117
	s_add_i32 s3, s3, 1
	v_mov_b32_e32 v117, v116
	s_cmp_ge_u32 s3, s18
	s_nop 0
	v_permlane32_swap_b32_e32 v116, v117
	s_cbranch_scc1 .Lat2_408
	v_max_f32_e32 v116, v116, v116
	v_max_f32_e32 v117, v117, v117
	v_max_f32_e32 v116, v116, v117
	v_cmp_lt_f32_e32 vcc, s88, v116
	s_cbranch_vccz .Lat2_408
	v_max_f32_e32 v116, v116, v116
	v_max_f32_e32 v117, 0, v116
	v_exp_f32_e64 v116, -v117
	v_sub_f32_e32 v115, v115, v117
	v_sub_f32_e32 v114, v114, v117
	v_sub_f32_e32 v113, v113, v117
	v_pk_mul_f32 v[82:83], v[82:83], v[116:117] op_sel_hi:[1,0]
	v_pk_mul_f32 v[80:81], v[80:81], v[116:117] op_sel_hi:[1,0]
	v_pk_mul_f32 v[78:79], v[78:79], v[116:117] op_sel_hi:[1,0]
	v_pk_mul_f32 v[76:77], v[76:77], v[116:117] op_sel_hi:[1,0]
	v_pk_mul_f32 v[74:75], v[74:75], v[116:117] op_sel_hi:[1,0]
	v_pk_mul_f32 v[72:73], v[72:73], v[116:117] op_sel_hi:[1,0]
	v_pk_mul_f32 v[70:71], v[70:71], v[116:117] op_sel_hi:[1,0]
	v_pk_mul_f32 v[68:69], v[68:69], v[116:117] op_sel_hi:[1,0]
	v_pk_mul_f32 v[66:67], v[66:67], v[116:117] op_sel_hi:[1,0]
	v_pk_mul_f32 v[64:65], v[64:65], v[116:117] op_sel_hi:[1,0]
	v_pk_mul_f32 v[62:63], v[62:63], v[116:117] op_sel_hi:[1,0]
	v_pk_mul_f32 v[60:61], v[60:61], v[116:117] op_sel_hi:[1,0]
	v_pk_mul_f32 v[58:59], v[58:59], v[116:117] op_sel_hi:[1,0]
	v_pk_mul_f32 v[56:57], v[56:57], v[116:117] op_sel_hi:[1,0]
	v_pk_mul_f32 v[54:55], v[54:55], v[116:117] op_sel_hi:[1,0]
	v_pk_mul_f32 v[52:53], v[52:53], v[116:117] op_sel_hi:[1,0]
	v_pk_mul_f32 v[50:51], v[50:51], v[116:117] op_sel_hi:[1,0]
	v_pk_mul_f32 v[48:49], v[48:49], v[116:117] op_sel_hi:[1,0]
	v_pk_mul_f32 v[46:47], v[46:47], v[116:117] op_sel_hi:[1,0]
	v_pk_mul_f32 v[44:45], v[44:45], v[116:117] op_sel_hi:[1,0]
	v_pk_mul_f32 v[42:43], v[42:43], v[116:117] op_sel_hi:[1,0]
	v_pk_mul_f32 v[40:41], v[40:41], v[116:117] op_sel_hi:[1,0]
	v_pk_mul_f32 v[38:39], v[38:39], v[116:117] op_sel_hi:[1,0]
	v_pk_mul_f32 v[36:37], v[36:37], v[116:117] op_sel_hi:[1,0]
	v_pk_mul_f32 v[34:35], v[34:35], v[116:117] op_sel_hi:[1,0]
	v_pk_mul_f32 v[32:33], v[32:33], v[116:117] op_sel_hi:[1,0]
	v_pk_mul_f32 v[30:31], v[30:31], v[116:117] op_sel_hi:[1,0]
	v_pk_mul_f32 v[28:29], v[28:29], v[116:117] op_sel_hi:[1,0]
	v_pk_mul_f32 v[26:27], v[26:27], v[116:117] op_sel_hi:[1,0]
	v_pk_mul_f32 v[24:25], v[24:25], v[116:117] op_sel_hi:[1,0]
	v_pk_mul_f32 v[22:23], v[22:23], v[116:117] op_sel_hi:[1,0]
	v_pk_mul_f32 v[20:21], v[20:21], v[116:117] op_sel_hi:[1,0]
	v_sub_f32_e32 v112, v112, v117
	v_sub_f32_e32 v111, v111, v117
	v_sub_f32_e32 v110, v110, v117
	v_sub_f32_e32 v109, v109, v117
	v_sub_f32_e32 v108, v108, v117
	v_sub_f32_e32 v107, v107, v117
	v_sub_f32_e32 v106, v106, v117
	v_sub_f32_e32 v105, v105, v117
	v_sub_f32_e32 v104, v104, v117
	v_sub_f32_e32 v103, v103, v117
	v_sub_f32_e32 v102, v102, v117
	v_sub_f32_e32 v101, v101, v117
	v_sub_f32_e32 v100, v100, v117
	v_sub_f32_e32 v99, v99, v117
	v_sub_f32_e32 v98, v98, v117
	v_sub_f32_e32 v97, v97, v117
	v_sub_f32_e32 v96, v96, v117
	v_sub_f32_e32 v95, v95, v117
	v_sub_f32_e32 v94, v94, v117
	v_sub_f32_e32 v93, v93, v117
	v_sub_f32_e32 v92, v92, v117
	v_sub_f32_e32 v91, v91, v117
	v_sub_f32_e32 v90, v90, v117
	v_sub_f32_e32 v89, v89, v117
	v_sub_f32_e32 v88, v88, v117
	v_sub_f32_e32 v87, v87, v117
	v_sub_f32_e32 v86, v86, v117
	v_sub_f32_e32 v85, v85, v117
	v_sub_f32_e32 v84, v84, v117
	v_sub_f32_e32 v19, v19, v117
	v_sub_f32_e32 v18, v18, v117
	v_sub_f32_e32 v17, v17, v117
	v_sub_f32_e32 v16, v16, v117
	v_sub_f32_e32 v15, v15, v117
	v_sub_f32_e32 v14, v14, v117
	v_sub_f32_e32 v13, v13, v117
	v_sub_f32_e32 v12, v12, v117
	v_sub_f32_e32 v11, v11, v117
	v_sub_f32_e32 v10, v10, v117
	v_sub_f32_e32 v9, v9, v117
	v_sub_f32_e32 v8, v8, v117
	v_sub_f32_e32 v7, v7, v117
	v_sub_f32_e32 v6, v6, v117
	v_sub_f32_e32 v5, v5, v117
	v_sub_f32_e32 v4, v4, v117
	v_mul_f32_e32 v197, v197, v116
